# grid barrier: non-leader workgroups poll the top-level arrival counter (released at (gen+1)*nx), skipping the generation-word hop
# speedup vs baseline: 1.1875x; 1.0065x over previous
.LBB0_77:
	s_or_b64 exec, exec, s[10:11]
	v_cvt_f32_u32_e32 v4, v2
	s_waitcnt vmcnt(0)
	v_readfirstlane_b32 s8, v3
	v_sub_u32_e32 v3, 0, v2
	v_rcp_iflag_f32_e32 v4, v4
	v_add_u32_e32 v5, s8, v1
	v_mul_f32_e32 v4, 0x4f7ffffe, v4
	v_cvt_u32_f32_e32 v4, v4
	v_mul_lo_u32 v1, v3, v4
	v_mul_hi_u32 v1, v4, v1
	v_add_u32_e32 v1, v4, v1
	v_mul_hi_u32 v1, v5, v1
	v_mul_lo_u32 v3, v1, v2
	v_sub_u32_e32 v3, v5, v3
	v_add_u32_e32 v4, 1, v1
	v_cmp_ge_u32_e32 vcc, v3, v2
	s_nop 1
	v_cndmask_b32_e32 v1, v1, v4, vcc
	v_sub_u32_e32 v4, v3, v2
	v_cndmask_b32_e32 v3, v3, v4, vcc
	v_add_u32_e32 v4, 1, v1
	v_cmp_ge_u32_e32 vcc, v3, v2
	v_add_u32_e32 v3, 1, v5
	s_nop 0
	v_cndmask_b32_e32 v1, v1, v4, vcc
	v_mul_lo_u32 v4, v2, v1
	v_add_u32_e32 v2, v4, v2
	v_cmp_ne_u32_e32 vcc, v3, v2
	s_and_saveexec_b64 s[8:9], vcc
	s_xor_b64 s[8:9], exec, s[8:9]
	s_cbranch_execz .LBB0_91
	v_readlane_b32 s14, v251, 12
	v_readlane_b32 s15, v251, 13
	v_mov_b32_e32 v0, 0x10804
	ds_read_b32 v0, v0
	v_add_u32_e32 v1, 1, v1
	s_waitcnt lgkmcnt(0)
	v_mul_lo_u32 v1, v1, v0
	v_mov_b32_e32 v0, 0
	s_nop 3
	s_add_u32 s14, s14, 0x3400
	s_addc_u32 s15, s15, 0
	global_load_dword v0, v0, s[14:15] sc1
	s_waitcnt vmcnt(0)
	v_cmp_gt_u32_e32 vcc, v1, v0
	s_and_saveexec_b64 s[10:11], vcc
	s_cbranch_execz .LBB0_90
	s_mov_b32 s12, 1
	s_mov_b64 s[16:17], 0
	v_mov_b32_e32 v0, 0
	s_branch .LBB0_81

.LBB0_86:
	global_load_dword v2, v0, s[14:15] sc1
	s_add_i32 s12, s12, 1
	s_mov_b64 s[22:23], -1
	s_waitcnt vmcnt(0)
	v_cmp_le_u32_e32 vcc, v1, v2
	s_orn2_b64 s[20:21], vcc, exec
	s_branch .LBB0_80

.LBB0_154:
	s_or_b64 exec, exec, s[8:9]
	v_cvt_f32_u32_e32 v4, v2
	s_waitcnt vmcnt(0)
	v_readfirstlane_b32 s3, v3
	v_sub_u32_e32 v3, 0, v2
	v_rcp_iflag_f32_e32 v4, v4
	v_add_u32_e32 v5, s3, v1
	v_mul_f32_e32 v4, 0x4f7ffffe, v4
	v_cvt_u32_f32_e32 v4, v4
	v_mul_lo_u32 v1, v3, v4
	v_mul_hi_u32 v1, v4, v1
	v_add_u32_e32 v1, v4, v1
	v_mul_hi_u32 v1, v5, v1
	v_mul_lo_u32 v3, v1, v2
	v_sub_u32_e32 v3, v5, v3
	v_add_u32_e32 v4, 1, v1
	v_cmp_ge_u32_e32 vcc, v3, v2
	s_nop 1
	v_cndmask_b32_e32 v1, v1, v4, vcc
	v_sub_u32_e32 v4, v3, v2
	v_cndmask_b32_e32 v3, v3, v4, vcc
	v_add_u32_e32 v4, 1, v1
	v_cmp_ge_u32_e32 vcc, v3, v2
	v_add_u32_e32 v3, 1, v5
	s_nop 0
	v_cndmask_b32_e32 v1, v1, v4, vcc
	v_mul_lo_u32 v4, v2, v1
	v_add_u32_e32 v2, v4, v2
	v_cmp_ne_u32_e32 vcc, v3, v2
	s_and_saveexec_b64 s[6:7], vcc
	s_xor_b64 s[6:7], exec, s[6:7]
	s_cbranch_execz .LBB0_168
	s_waitcnt lgkmcnt(0)
	v_readlane_b32 s10, v251, 12
	v_readlane_b32 s11, v251, 13
	v_mov_b32_e32 v0, 0x10804
	ds_read_b32 v0, v0
	v_add_u32_e32 v1, 1, v1
	s_waitcnt lgkmcnt(0)
	v_mul_lo_u32 v1, v1, v0
	v_mov_b32_e32 v0, 0
	s_nop 3
	s_add_u32 s10, s10, 0x3400
	s_addc_u32 s11, s11, 0
	global_load_dword v0, v0, s[10:11] sc1
	s_waitcnt vmcnt(0)
	v_cmp_gt_u32_e32 vcc, v1, v0
	s_and_saveexec_b64 s[8:9], vcc
	s_cbranch_execz .LBB0_167
	s_mov_b32 s3, 1
	s_mov_b64 s[14:15], 0
	v_mov_b32_e32 v0, 0
	s_branch .LBB0_158

.LBB0_162:
	global_load_dword v2, v0, s[10:11] sc1
	s_add_i32 s3, s3, 1
	s_mov_b64 s[22:23], -1
	s_waitcnt vmcnt(0)
	v_cmp_le_u32_e32 vcc, v1, v2
	s_orn2_b64 s[18:19], vcc, exec
	s_branch .LBB0_157

.LBB0_485:
	s_or_b64 exec, exec, s[14:15]
	v_cvt_f32_u32_e32 v4, v2
	s_waitcnt vmcnt(0)
	v_readfirstlane_b32 s3, v3
	v_sub_u32_e32 v3, 0, v2
	v_rcp_iflag_f32_e32 v4, v4
	v_add_u32_e32 v5, s3, v1
	v_mul_f32_e32 v4, 0x4f7ffffe, v4
	v_cvt_u32_f32_e32 v4, v4
	v_mul_lo_u32 v1, v3, v4
	v_mul_hi_u32 v1, v4, v1
	v_add_u32_e32 v1, v4, v1
	v_mul_hi_u32 v1, v5, v1
	v_mul_lo_u32 v3, v1, v2
	v_sub_u32_e32 v3, v5, v3
	v_add_u32_e32 v4, 1, v1
	v_cmp_ge_u32_e32 vcc, v3, v2
	s_nop 1
	v_cndmask_b32_e32 v1, v1, v4, vcc
	v_sub_u32_e32 v4, v3, v2
	v_cndmask_b32_e32 v3, v3, v4, vcc
	v_add_u32_e32 v4, 1, v1
	v_cmp_ge_u32_e32 vcc, v3, v2
	v_add_u32_e32 v3, 1, v5
	s_nop 0
	v_cndmask_b32_e32 v1, v1, v4, vcc
	v_mul_lo_u32 v4, v2, v1
	v_add_u32_e32 v2, v4, v2
	v_cmp_ne_u32_e32 vcc, v3, v2
	s_and_saveexec_b64 s[4:5], vcc
	s_xor_b64 s[10:11], exec, s[4:5]
	s_cbranch_execz .LBB0_499
	s_waitcnt lgkmcnt(0)
	v_readlane_b32 s16, v251, 12
	v_readlane_b32 s17, v251, 13
	v_mov_b32_e32 v0, 0x10804
	ds_read_b32 v0, v0
	v_add_u32_e32 v1, 1, v1
	s_waitcnt lgkmcnt(0)
	v_mul_lo_u32 v1, v1, v0
	v_mov_b32_e32 v0, 0
	s_nop 3
	s_add_u32 s16, s16, 0x3400
	s_addc_u32 s17, s17, 0
	global_load_dword v0, v0, s[16:17] sc1
	s_waitcnt vmcnt(0)
	v_cmp_gt_u32_e32 vcc, v1, v0
	s_and_saveexec_b64 s[14:15], vcc
	s_cbranch_execz .LBB0_498
	s_mov_b32 s3, 1
	s_mov_b64 s[18:19], 0
	v_mov_b32_e32 v0, 0
	s_branch .LBB0_489

.LBB0_493:
	global_load_dword v2, v0, s[16:17] sc1
	s_add_i32 s3, s3, 1
	s_mov_b64 s[26:27], -1
	s_waitcnt vmcnt(0)
	v_cmp_le_u32_e32 vcc, v1, v2
	s_orn2_b64 s[24:25], vcc, exec
	s_branch .LBB0_488

.LBB0_707:
	s_or_b64 exec, exec, s[8:9]
	v_cvt_f32_u32_e32 v4, v2
	s_waitcnt vmcnt(0)
	v_readfirstlane_b32 s6, v3
	v_sub_u32_e32 v3, 0, v2
	v_rcp_iflag_f32_e32 v4, v4
	v_add_u32_e32 v5, s6, v1
	v_mul_f32_e32 v4, 0x4f7ffffe, v4
	v_cvt_u32_f32_e32 v4, v4
	v_mul_lo_u32 v1, v3, v4
	v_mul_hi_u32 v1, v4, v1
	v_add_u32_e32 v1, v4, v1
	v_mul_hi_u32 v1, v5, v1
	v_mul_lo_u32 v3, v1, v2
	v_sub_u32_e32 v3, v5, v3
	v_add_u32_e32 v4, 1, v1
	v_cmp_ge_u32_e32 vcc, v3, v2
	s_nop 1
	v_cndmask_b32_e32 v1, v1, v4, vcc
	v_sub_u32_e32 v4, v3, v2
	v_cndmask_b32_e32 v3, v3, v4, vcc
	v_add_u32_e32 v4, 1, v1
	v_cmp_ge_u32_e32 vcc, v3, v2
	v_add_u32_e32 v3, 1, v5
	s_nop 0
	v_cndmask_b32_e32 v1, v1, v4, vcc
	v_mul_lo_u32 v4, v2, v1
	v_add_u32_e32 v2, v4, v2
	v_cmp_ne_u32_e32 vcc, v3, v2
	s_and_saveexec_b64 s[6:7], vcc
	s_xor_b64 s[6:7], exec, s[6:7]
	s_cbranch_execz .LBB0_721
	s_waitcnt lgkmcnt(0)
	v_readlane_b32 s10, v251, 12
	v_readlane_b32 s11, v251, 13
	v_mov_b32_e32 v0, 0x10804
	ds_read_b32 v0, v0
	v_add_u32_e32 v1, 1, v1
	s_waitcnt lgkmcnt(0)
	v_mul_lo_u32 v1, v1, v0
	v_mov_b32_e32 v0, 0
	s_nop 3
	s_add_u32 s10, s10, 0x3400
	s_addc_u32 s11, s11, 0
	global_load_dword v0, v0, s[10:11] sc1
	s_waitcnt vmcnt(0)
	v_cmp_gt_u32_e32 vcc, v1, v0
	s_and_saveexec_b64 s[8:9], vcc
	s_cbranch_execz .LBB0_720
	s_mov_b32 s28, 1
	s_mov_b64 s[16:17], 0
	v_mov_b32_e32 v0, 0
	s_branch .LBB0_711

.LBB0_715:
	global_load_dword v2, v0, s[10:11] sc1
	s_add_i32 s28, s28, 1
	s_mov_b64 s[24:25], -1
	s_waitcnt vmcnt(0)
	v_cmp_le_u32_e32 vcc, v1, v2
	s_orn2_b64 s[22:23], vcc, exec
	s_branch .LBB0_710

.LBB0_762:
	s_or_b64 exec, exec, s[8:9]
	v_cvt_f32_u32_e32 v4, v2
	s_waitcnt vmcnt(0)
	v_readfirstlane_b32 s6, v3
	v_sub_u32_e32 v3, 0, v2
	v_rcp_iflag_f32_e32 v4, v4
	v_add_u32_e32 v5, s6, v1
	v_mul_f32_e32 v4, 0x4f7ffffe, v4
	v_cvt_u32_f32_e32 v4, v4
	v_mul_lo_u32 v1, v3, v4
	v_mul_hi_u32 v1, v4, v1
	v_add_u32_e32 v1, v4, v1
	v_mul_hi_u32 v1, v5, v1
	v_mul_lo_u32 v3, v1, v2
	v_sub_u32_e32 v3, v5, v3
	v_add_u32_e32 v4, 1, v1
	v_cmp_ge_u32_e32 vcc, v3, v2
	s_nop 1
	v_cndmask_b32_e32 v1, v1, v4, vcc
	v_sub_u32_e32 v4, v3, v2
	v_cndmask_b32_e32 v3, v3, v4, vcc
	v_add_u32_e32 v4, 1, v1
	v_cmp_ge_u32_e32 vcc, v3, v2
	v_add_u32_e32 v3, 1, v5
	s_nop 0
	v_cndmask_b32_e32 v1, v1, v4, vcc
	v_mul_lo_u32 v4, v2, v1
	v_add_u32_e32 v2, v4, v2
	v_cmp_ne_u32_e32 vcc, v3, v2
	s_and_saveexec_b64 s[6:7], vcc
	s_xor_b64 s[6:7], exec, s[6:7]
	s_cbranch_execz .LBB0_776
	s_waitcnt lgkmcnt(0)
	v_readlane_b32 s10, v251, 12
	v_readlane_b32 s11, v251, 13
	v_mov_b32_e32 v0, 0x10804
	ds_read_b32 v0, v0
	v_add_u32_e32 v1, 1, v1
	s_waitcnt lgkmcnt(0)
	v_mul_lo_u32 v1, v1, v0
	v_mov_b32_e32 v0, 0
	s_nop 3
	s_add_u32 s10, s10, 0x3400
	s_addc_u32 s11, s11, 0
	global_load_dword v0, v0, s[10:11] sc1
	s_waitcnt vmcnt(0)
	v_cmp_gt_u32_e32 vcc, v1, v0
	s_and_saveexec_b64 s[8:9], vcc
	s_cbranch_execz .LBB0_775
	s_mov_b32 s30, 1
	s_mov_b64 s[18:19], 0
	v_mov_b32_e32 v0, 0
	s_branch .LBB0_766

.LBB0_770:
	global_load_dword v2, v0, s[10:11] sc1
	s_add_i32 s30, s30, 1
	s_mov_b64 s[26:27], -1
	s_waitcnt vmcnt(0)
	v_cmp_le_u32_e32 vcc, v1, v2
	s_orn2_b64 s[24:25], vcc, exec
	s_branch .LBB0_765

.LBB0_873:
	s_or_b64 exec, exec, s[8:9]
	v_cvt_f32_u32_e32 v4, v2
	s_waitcnt vmcnt(0)
	v_readfirstlane_b32 s6, v3
	v_sub_u32_e32 v3, 0, v2
	v_rcp_iflag_f32_e32 v4, v4
	v_add_u32_e32 v5, s6, v1
	v_mul_f32_e32 v4, 0x4f7ffffe, v4
	v_cvt_u32_f32_e32 v4, v4
	v_mul_lo_u32 v1, v3, v4
	v_mul_hi_u32 v1, v4, v1
	v_add_u32_e32 v1, v4, v1
	v_mul_hi_u32 v1, v5, v1
	v_mul_lo_u32 v3, v1, v2
	v_sub_u32_e32 v3, v5, v3
	v_add_u32_e32 v4, 1, v1
	v_cmp_ge_u32_e32 vcc, v3, v2
	s_nop 1
	v_cndmask_b32_e32 v1, v1, v4, vcc
	v_sub_u32_e32 v4, v3, v2
	v_cndmask_b32_e32 v3, v3, v4, vcc
	v_add_u32_e32 v4, 1, v1
	v_cmp_ge_u32_e32 vcc, v3, v2
	v_add_u32_e32 v3, 1, v5
	s_nop 0
	v_cndmask_b32_e32 v1, v1, v4, vcc
	v_mul_lo_u32 v4, v2, v1
	v_add_u32_e32 v2, v4, v2
	v_cmp_ne_u32_e32 vcc, v3, v2
	s_and_saveexec_b64 s[6:7], vcc
	s_xor_b64 s[6:7], exec, s[6:7]
	s_cbranch_execz .LBB0_887
	s_waitcnt lgkmcnt(0)
	v_readlane_b32 s10, v251, 12
	v_readlane_b32 s11, v251, 13
	v_mov_b32_e32 v0, 0x10804
	ds_read_b32 v0, v0
	v_add_u32_e32 v1, 1, v1
	s_waitcnt lgkmcnt(0)
	v_mul_lo_u32 v1, v1, v0
	v_mov_b32_e32 v0, 0
	s_nop 3
	s_add_u32 s10, s10, 0x3400
	s_addc_u32 s11, s11, 0
	global_load_dword v0, v0, s[10:11] sc1
	s_waitcnt vmcnt(0)
	v_cmp_gt_u32_e32 vcc, v1, v0
	s_and_saveexec_b64 s[8:9], vcc
	s_cbranch_execz .LBB0_886
	s_mov_b32 s28, 1
	s_mov_b64 s[18:19], 0
	v_mov_b32_e32 v0, 0
	s_branch .LBB0_877

.LBB0_945:
	s_or_b64 exec, exec, s[8:9]
	v_cvt_f32_u32_e32 v4, v2
	s_waitcnt vmcnt(0)
	v_readfirstlane_b32 s3, v3
	v_sub_u32_e32 v3, 0, v2
	v_rcp_iflag_f32_e32 v4, v4
	v_add_u32_e32 v5, s3, v1
	v_mul_f32_e32 v4, 0x4f7ffffe, v4
	v_cvt_u32_f32_e32 v4, v4
	v_mul_lo_u32 v1, v3, v4
	v_mul_hi_u32 v1, v4, v1
	v_add_u32_e32 v1, v4, v1
	v_mul_hi_u32 v1, v5, v1
	v_mul_lo_u32 v3, v1, v2
	v_sub_u32_e32 v3, v5, v3
	v_add_u32_e32 v4, 1, v1
	v_cmp_ge_u32_e32 vcc, v3, v2
	s_nop 1
	v_cndmask_b32_e32 v1, v1, v4, vcc
	v_sub_u32_e32 v4, v3, v2
	v_cndmask_b32_e32 v3, v3, v4, vcc
	v_add_u32_e32 v4, 1, v1
	v_cmp_ge_u32_e32 vcc, v3, v2
	v_add_u32_e32 v3, 1, v5
	s_nop 0
	v_cndmask_b32_e32 v1, v1, v4, vcc
	v_mul_lo_u32 v4, v2, v1
	v_add_u32_e32 v2, v4, v2
	v_cmp_ne_u32_e32 vcc, v3, v2
	s_and_saveexec_b64 s[6:7], vcc
	s_xor_b64 s[6:7], exec, s[6:7]
	s_cbranch_execz .LBB0_959
	s_waitcnt lgkmcnt(0)
	v_readlane_b32 s10, v251, 12
	v_readlane_b32 s11, v251, 13
	v_mov_b32_e32 v0, 0x10804
	ds_read_b32 v0, v0
	v_add_u32_e32 v1, 1, v1
	s_waitcnt lgkmcnt(0)
	v_mul_lo_u32 v1, v1, v0
	v_mov_b32_e32 v0, 0
	s_nop 3
	s_add_u32 s10, s10, 0x3400
	s_addc_u32 s11, s11, 0
	global_load_dword v0, v0, s[10:11] sc1
	s_waitcnt vmcnt(0)
	v_cmp_gt_u32_e32 vcc, v1, v0
	s_and_saveexec_b64 s[8:9], vcc
	s_cbranch_execz .LBB0_958
	s_mov_b32 s3, 1
	s_mov_b64 s[12:13], 0
	v_mov_b32_e32 v0, 0
	s_branch .LBB0_949

.LBB0_953:
	global_load_dword v2, v0, s[10:11] sc1
	s_add_i32 s3, s3, 1
	s_mov_b64 s[20:21], -1
	s_waitcnt vmcnt(0)
	v_cmp_le_u32_e32 vcc, v1, v2
	s_orn2_b64 s[18:19], vcc, exec
	s_branch .LBB0_948
